# group-norm rescale fused into the end of each ssd_out item (per-wave, in place); sample-row group norm done by WG0 at phase entry; gnorm phase and its grid barrier skipped
# speedup vs baseline: 1.0601x; 1.0064x over previous
.LBB0_11:
	s_cmp_eq_u32 s10, 5
	s_cselect_b32 s10, 6, s10
	s_mov_b64 s[68:69], s[78:79]
	s_mov_b32 s0, s10
	s_ashr_i32 s1, s10, 31
	s_load_dwordx2 s[24:25], s[68:69], 0xc8
	s_lshl_b64 s[0:1], s[0:1], 2
	s_getpc_b64 s[4:5]
	s_add_u32 s4, s4, _ZL4PROG@rel32@lo+4
	s_addc_u32 s5, s5, _ZL4PROG@rel32@hi+12
	s_add_u32 s0, s4, s0
	s_mov_b32 s2, s10
	s_addc_u32 s1, s5, s1
	v_writelane_b32 v255, s2, 30
	s_load_dword s91, s[0:1], 0x0
	s_waitcnt lgkmcnt(0)
	s_add_u32 s0, s24, 0x11900200
	v_writelane_b32 v255, s3, 31
	s_addc_u32 s1, s25, 0
	v_writelane_b32 v255, s0, 32
	s_add_u32 s82, s24, 0x13c59800
	s_addc_u32 s83, s25, 0
	v_writelane_b32 v255, s1, 33
	s_mov_b64 s[0:1], 0
	v_writelane_b32 v255, s0, 34
	s_mov_b64 s[4:5], -1
	s_cmp_lt_i32 s91, 9
	v_writelane_b32 v255, s1, 35
	s_mov_b64 s[26:27], 0
	s_mov_b64 s[0:1], 0
	v_writelane_b32 v255, s0, 36
	s_nop 1
	v_writelane_b32 v255, s1, 37
	s_cbranch_scc1 .LBB0_182
	s_cmp_gt_i32 s91, 13
	s_cbranch_scc0 .LBB0_19
	s_cmp_gt_i32 s91, 15
	s_mov_b64 s[0:1], 0
	v_writelane_b32 v255, s0, 36
	s_nop 1
	v_writelane_b32 v255, s1, 37
	s_cbranch_scc0 .LBB0_44
	s_cmp_gt_i32 s91, 16
	s_cbranch_scc0 .LBB0_37
	s_cmp_gt_i32 s91, 17
	s_mov_b64 s[6:7], -1
	s_cbranch_scc0 .LBB0_39
	s_cmp_eq_u32 s91, 18
	s_cbranch_scc0 .LBB0_38
	s_waitcnt vmcnt(1)
	v_mov_b32_e32 v0, v177
	v_readlane_b32 s1, v254, 0
	s_lshl_b32 s1, s1, 3
	v_readfirstlane_b32 s0, v0
	s_ashr_i32 s0, s0, 6
	s_add_i32 s4, s1, s0
	s_cmpk_gt_i32 s4, 0x2007
	s_cbranch_scc1 .LBB0_38
	s_load_dwordx4 s[40:43], s[68:69], 0xb8
	v_lshlrev_b32_e32 v1, 2, v0
	v_and_b32_e32 v0, 0xfc, v1
	s_load_dword s0, s[74:75], 0x0
	v_lshlrev_b32_e32 v172, 2, v0
	v_or_b32_e32 v72, 0x400, v0
	v_lshl_add_u64 v[2:3], s[24:25], 0, v[172:173]
	s_waitcnt lgkmcnt(0)
	v_lshl_add_u64 v[70:71], s[40:41], 0, v[172:173]
	v_lshlrev_b32_e32 v172, 2, v72
	v_or_b32_e32 v76, 0x500, v0
	v_lshl_add_u64 v[74:75], s[40:41], 0, v[172:173]
	v_lshlrev_b32_e32 v172, 2, v76
	v_or_b32_e32 v80, 0x600, v0
	v_lshl_add_u64 v[78:79], s[40:41], 0, v[172:173]
	v_lshlrev_b32_e32 v172, 2, v80
	v_or_b32_e32 v84, 0x700, v0
	s_mov_b64 s[6:7], 0xd700200
	v_lshl_add_u64 v[82:83], s[40:41], 0, v[172:173]
	v_lshlrev_b32_e32 v172, 2, v84
	s_lshl_b32 s0, s0, 3
	v_lshl_add_u64 v[68:69], v[2:3], 0, s[6:7]
	v_bitop3_b32 v73, v1, s97, v223 bitop3:0x6c
	v_bitop3_b32 v77, v1, 64, v223 bitop3:0x6c
	v_bitop3_b32 v81, v1, 32, v223 bitop3:0x6c
	v_bitop3_b32 v85, v1, 16, v223 bitop3:0x6c
	v_bitop3_b32 v92, v1, 8, v223 bitop3:0x6c
	v_bitop3_b32 v93, v1, 4, v223 bitop3:0x6c
	v_lshl_add_u64 v[86:87], s[40:41], 0, v[172:173]
	v_lshlrev_b32_e32 v172, 2, v0
	s_branch .LBB0_21

.LBB0_253:
	s_andn2_b64 vcc, exec, s[4:5]
	s_cbranch_vccnz .LBB0_430
	v_readlane_b32 s92, v254, 0
	s_cmp_lg_u32 s92, 0
	s_cbranch_scc1 .Lsg_skip
	v_lshrrev_b32_e32 v140, 6, v177
	v_and_b32_e32 v141, 63, v177
	v_readfirstlane_b32 s98, v140
	v_lshlrev_b32_e32 v140, 2, v141
	v_lshlrev_b32_e32 v141, 4, v141
	s_add_i32 s98, s98, 0x2000
	s_mul_i32 s100, s98, 0x5200
	s_mul_hi_i32 s101, s98, 0x5200
	s_add_u32 s100, s82, s100
	s_addc_u32 s101, s83, s101
	s_add_u32 s98, s100, 0x1000
	s_addc_u32 s99, s101, 0
	global_load_dwordx4 v[144:147], v141, s[100:101]
	global_load_dwordx4 v[148:151], v141, s[100:101] offset:1024
	global_load_dwordx4 v[152:155], v141, s[100:101] offset:2048
	global_load_dwordx4 v[156:159], v141, s[100:101] offset:3072
	global_load_dwordx4 v[160:163], v141, s[98:99]
	global_load_dwordx4 v[164:167], v141, s[98:99] offset:1024
	global_load_dwordx4 v[168:171], v141, s[98:99] offset:2048
	global_load_dwordx4 v[182:185], v141, s[98:99] offset:3072
	v_xor_b32_e32 v204, 0x80, v140
	v_xor_b32_e32 v205, 0x40, v140
	v_xor_b32_e32 v206, 0x20, v140
	v_xor_b32_e32 v207, 0x10, v140
	v_xor_b32_e32 v208, 0x8, v140
	v_xor_b32_e32 v209, 0x4, v140
	s_waitcnt vmcnt(0)
	v_and_b32_e32 v210, 0xffff0000, v144
	v_lshlrev_b32_e32 v211, 16, v144
	v_mul_f32_e32 v142, v210, v210
	v_fmac_f32_e32 v142, v211, v211
	v_and_b32_e32 v210, 0xffff0000, v145
	v_lshlrev_b32_e32 v211, 16, v145
	v_mul_f32_e32 v143, v210, v210
	v_fmac_f32_e32 v143, v211, v211
	v_and_b32_e32 v210, 0xffff0000, v146
	v_lshlrev_b32_e32 v211, 16, v146
	v_mul_f32_e32 v218, v210, v210
	v_fmac_f32_e32 v218, v211, v211
	v_and_b32_e32 v210, 0xffff0000, v147
	v_lshlrev_b32_e32 v211, 16, v147
	v_mul_f32_e32 v219, v210, v210
	v_fmac_f32_e32 v219, v211, v211
	v_add_f32_e32 v196, v142, v143
	v_add_f32_e32 v196, v218, v196
	v_add_f32_e32 v196, v219, v196
	v_and_b32_e32 v210, 0xffff0000, v148
	v_lshlrev_b32_e32 v211, 16, v148
	v_mul_f32_e32 v142, v210, v210
	v_fmac_f32_e32 v142, v211, v211
	v_and_b32_e32 v210, 0xffff0000, v149
	v_lshlrev_b32_e32 v211, 16, v149
	v_mul_f32_e32 v143, v210, v210
	v_fmac_f32_e32 v143, v211, v211
	v_and_b32_e32 v210, 0xffff0000, v150
	v_lshlrev_b32_e32 v211, 16, v150
	v_mul_f32_e32 v218, v210, v210
	v_fmac_f32_e32 v218, v211, v211
	v_and_b32_e32 v210, 0xffff0000, v151
	v_lshlrev_b32_e32 v211, 16, v151
	v_mul_f32_e32 v219, v210, v210
	v_fmac_f32_e32 v219, v211, v211
	v_add_f32_e32 v197, v142, v143
	v_add_f32_e32 v197, v218, v197
	v_add_f32_e32 v197, v219, v197
	v_and_b32_e32 v210, 0xffff0000, v152
	v_lshlrev_b32_e32 v211, 16, v152
	v_mul_f32_e32 v142, v210, v210
	v_fmac_f32_e32 v142, v211, v211
	v_and_b32_e32 v210, 0xffff0000, v153
	v_lshlrev_b32_e32 v211, 16, v153
	v_mul_f32_e32 v143, v210, v210
	v_fmac_f32_e32 v143, v211, v211
	v_and_b32_e32 v210, 0xffff0000, v154
	v_lshlrev_b32_e32 v211, 16, v154
	v_mul_f32_e32 v218, v210, v210
	v_fmac_f32_e32 v218, v211, v211
	v_and_b32_e32 v210, 0xffff0000, v155
	v_lshlrev_b32_e32 v211, 16, v155
	v_mul_f32_e32 v219, v210, v210
	v_fmac_f32_e32 v219, v211, v211
	v_add_f32_e32 v198, v142, v143
	v_add_f32_e32 v198, v218, v198
	v_add_f32_e32 v198, v219, v198
	v_and_b32_e32 v210, 0xffff0000, v156
	v_lshlrev_b32_e32 v211, 16, v156
	v_mul_f32_e32 v142, v210, v210
	v_fmac_f32_e32 v142, v211, v211
	v_and_b32_e32 v210, 0xffff0000, v157
	v_lshlrev_b32_e32 v211, 16, v157
	v_mul_f32_e32 v143, v210, v210
	v_fmac_f32_e32 v143, v211, v211
	v_and_b32_e32 v210, 0xffff0000, v158
	v_lshlrev_b32_e32 v211, 16, v158
	v_mul_f32_e32 v218, v210, v210
	v_fmac_f32_e32 v218, v211, v211
	v_and_b32_e32 v210, 0xffff0000, v159
	v_lshlrev_b32_e32 v211, 16, v159
	v_mul_f32_e32 v219, v210, v210
	v_fmac_f32_e32 v219, v211, v211
	v_add_f32_e32 v199, v142, v143
	v_add_f32_e32 v199, v218, v199
	v_add_f32_e32 v199, v219, v199
	v_and_b32_e32 v210, 0xffff0000, v160
	v_lshlrev_b32_e32 v211, 16, v160
	v_mul_f32_e32 v142, v210, v210
	v_fmac_f32_e32 v142, v211, v211
	v_and_b32_e32 v210, 0xffff0000, v161
	v_lshlrev_b32_e32 v211, 16, v161
	v_mul_f32_e32 v143, v210, v210
	v_fmac_f32_e32 v143, v211, v211
	v_and_b32_e32 v210, 0xffff0000, v162
	v_lshlrev_b32_e32 v211, 16, v162
	v_mul_f32_e32 v218, v210, v210
	v_fmac_f32_e32 v218, v211, v211
	v_and_b32_e32 v210, 0xffff0000, v163
	v_lshlrev_b32_e32 v211, 16, v163
	v_mul_f32_e32 v219, v210, v210
	v_fmac_f32_e32 v219, v211, v211
	v_add_f32_e32 v200, v142, v143
	v_add_f32_e32 v200, v218, v200
	v_add_f32_e32 v200, v219, v200
	v_and_b32_e32 v210, 0xffff0000, v164
	v_lshlrev_b32_e32 v211, 16, v164
	v_mul_f32_e32 v142, v210, v210
	v_fmac_f32_e32 v142, v211, v211
	v_and_b32_e32 v210, 0xffff0000, v165
	v_lshlrev_b32_e32 v211, 16, v165
	v_mul_f32_e32 v143, v210, v210
	v_fmac_f32_e32 v143, v211, v211
	v_and_b32_e32 v210, 0xffff0000, v166
	v_lshlrev_b32_e32 v211, 16, v166
	v_mul_f32_e32 v218, v210, v210
	v_fmac_f32_e32 v218, v211, v211
	v_and_b32_e32 v210, 0xffff0000, v167
	v_lshlrev_b32_e32 v211, 16, v167
	v_mul_f32_e32 v219, v210, v210
	v_fmac_f32_e32 v219, v211, v211
	v_add_f32_e32 v201, v142, v143
	v_add_f32_e32 v201, v218, v201
	v_add_f32_e32 v201, v219, v201
	v_and_b32_e32 v210, 0xffff0000, v168
	v_lshlrev_b32_e32 v211, 16, v168
	v_mul_f32_e32 v142, v210, v210
	v_fmac_f32_e32 v142, v211, v211
	v_and_b32_e32 v210, 0xffff0000, v169
	v_lshlrev_b32_e32 v211, 16, v169
	v_mul_f32_e32 v143, v210, v210
	v_fmac_f32_e32 v143, v211, v211
	v_and_b32_e32 v210, 0xffff0000, v170
	v_lshlrev_b32_e32 v211, 16, v170
	v_mul_f32_e32 v218, v210, v210
	v_fmac_f32_e32 v218, v211, v211
	v_and_b32_e32 v210, 0xffff0000, v171
	v_lshlrev_b32_e32 v211, 16, v171
	v_mul_f32_e32 v219, v210, v210
	v_fmac_f32_e32 v219, v211, v211
	v_add_f32_e32 v202, v142, v143
	v_add_f32_e32 v202, v218, v202
	v_add_f32_e32 v202, v219, v202
	v_and_b32_e32 v210, 0xffff0000, v182
	v_lshlrev_b32_e32 v211, 16, v182
	v_mul_f32_e32 v142, v210, v210
	v_fmac_f32_e32 v142, v211, v211
	v_and_b32_e32 v210, 0xffff0000, v183
	v_lshlrev_b32_e32 v211, 16, v183
	v_mul_f32_e32 v143, v210, v210
	v_fmac_f32_e32 v143, v211, v211
	v_and_b32_e32 v210, 0xffff0000, v184
	v_lshlrev_b32_e32 v211, 16, v184
	v_mul_f32_e32 v218, v210, v210
	v_fmac_f32_e32 v218, v211, v211
	v_and_b32_e32 v210, 0xffff0000, v185
	v_lshlrev_b32_e32 v211, 16, v185
	v_mul_f32_e32 v219, v210, v210
	v_fmac_f32_e32 v219, v211, v211
	v_add_f32_e32 v203, v142, v143
	v_add_f32_e32 v203, v218, v203
	v_add_f32_e32 v203, v219, v203
	ds_bpermute_b32 v210, v204, v196
	ds_bpermute_b32 v211, v204, v197
	ds_bpermute_b32 v212, v204, v198
	ds_bpermute_b32 v213, v204, v199
	ds_bpermute_b32 v214, v204, v200
	ds_bpermute_b32 v215, v204, v201
	ds_bpermute_b32 v216, v204, v202
	ds_bpermute_b32 v217, v204, v203
	s_waitcnt lgkmcnt(0)
	v_add_f32_e32 v196, v196, v210
	v_add_f32_e32 v197, v197, v211
	v_add_f32_e32 v198, v198, v212
	v_add_f32_e32 v199, v199, v213
	v_add_f32_e32 v200, v200, v214
	v_add_f32_e32 v201, v201, v215
	v_add_f32_e32 v202, v202, v216
	v_add_f32_e32 v203, v203, v217
	ds_bpermute_b32 v210, v205, v196
	ds_bpermute_b32 v211, v205, v197
	ds_bpermute_b32 v212, v205, v198
	ds_bpermute_b32 v213, v205, v199
	ds_bpermute_b32 v214, v205, v200
	ds_bpermute_b32 v215, v205, v201
	ds_bpermute_b32 v216, v205, v202
	ds_bpermute_b32 v217, v205, v203
	s_waitcnt lgkmcnt(0)
	v_add_f32_e32 v196, v196, v210
	v_add_f32_e32 v197, v197, v211
	v_add_f32_e32 v198, v198, v212
	v_add_f32_e32 v199, v199, v213
	v_add_f32_e32 v200, v200, v214
	v_add_f32_e32 v201, v201, v215
	v_add_f32_e32 v202, v202, v216
	v_add_f32_e32 v203, v203, v217
	ds_bpermute_b32 v210, v206, v196
	ds_bpermute_b32 v211, v206, v197
	ds_bpermute_b32 v212, v206, v198
	ds_bpermute_b32 v213, v206, v199
	ds_bpermute_b32 v214, v206, v200
	ds_bpermute_b32 v215, v206, v201
	ds_bpermute_b32 v216, v206, v202
	ds_bpermute_b32 v217, v206, v203
	s_waitcnt lgkmcnt(0)
	v_add_f32_e32 v196, v196, v210
	v_add_f32_e32 v197, v197, v211
	v_add_f32_e32 v198, v198, v212
	v_add_f32_e32 v199, v199, v213
	v_add_f32_e32 v200, v200, v214
	v_add_f32_e32 v201, v201, v215
	v_add_f32_e32 v202, v202, v216
	v_add_f32_e32 v203, v203, v217
	ds_bpermute_b32 v210, v207, v196
	ds_bpermute_b32 v211, v207, v197
	ds_bpermute_b32 v212, v207, v198
	ds_bpermute_b32 v213, v207, v199
	ds_bpermute_b32 v214, v207, v200
	ds_bpermute_b32 v215, v207, v201
	ds_bpermute_b32 v216, v207, v202
	ds_bpermute_b32 v217, v207, v203
	s_waitcnt lgkmcnt(0)
	v_add_f32_e32 v196, v196, v210
	v_add_f32_e32 v197, v197, v211
	v_add_f32_e32 v198, v198, v212
	v_add_f32_e32 v199, v199, v213
	v_add_f32_e32 v200, v200, v214
	v_add_f32_e32 v201, v201, v215
	v_add_f32_e32 v202, v202, v216
	v_add_f32_e32 v203, v203, v217
	ds_bpermute_b32 v210, v208, v196
	ds_bpermute_b32 v211, v208, v197
	ds_bpermute_b32 v212, v208, v198
	ds_bpermute_b32 v213, v208, v199
	ds_bpermute_b32 v214, v208, v200
	ds_bpermute_b32 v215, v208, v201
	ds_bpermute_b32 v216, v208, v202
	ds_bpermute_b32 v217, v208, v203
	s_waitcnt lgkmcnt(0)
	v_add_f32_e32 v196, v196, v210
	v_add_f32_e32 v197, v197, v211
	v_add_f32_e32 v198, v198, v212
	v_add_f32_e32 v199, v199, v213
	v_add_f32_e32 v200, v200, v214
	v_add_f32_e32 v201, v201, v215
	v_add_f32_e32 v202, v202, v216
	v_add_f32_e32 v203, v203, v217
	ds_bpermute_b32 v210, v209, v196
	ds_bpermute_b32 v211, v209, v197
	ds_bpermute_b32 v212, v209, v198
	ds_bpermute_b32 v213, v209, v199
	ds_bpermute_b32 v214, v209, v200
	ds_bpermute_b32 v215, v209, v201
	ds_bpermute_b32 v216, v209, v202
	ds_bpermute_b32 v217, v209, v203
	s_waitcnt lgkmcnt(0)
	v_add_f32_e32 v196, v196, v210
	v_add_f32_e32 v197, v197, v211
	v_add_f32_e32 v198, v198, v212
	v_add_f32_e32 v199, v199, v213
	v_add_f32_e32 v200, v200, v214
	v_add_f32_e32 v201, v201, v215
	v_add_f32_e32 v202, v202, v216
	v_add_f32_e32 v203, v203, v217
	v_fmamk_f32 v196, v196, 0x3b000000, v176
	v_rsq_f32_e32 v196, v196
	v_fmamk_f32 v197, v197, 0x3b000000, v176
	v_rsq_f32_e32 v197, v197
	v_fmamk_f32 v198, v198, 0x3b000000, v176
	v_rsq_f32_e32 v198, v198
	v_fmamk_f32 v199, v199, 0x3b000000, v176
	v_rsq_f32_e32 v199, v199
	v_fmamk_f32 v200, v200, 0x3b000000, v176
	v_rsq_f32_e32 v200, v200
	v_fmamk_f32 v201, v201, 0x3b000000, v176
	v_rsq_f32_e32 v201, v201
	v_fmamk_f32 v202, v202, 0x3b000000, v176
	v_rsq_f32_e32 v202, v202
	v_fmamk_f32 v203, v203, 0x3b000000, v176
	v_rsq_f32_e32 v203, v203
	s_nop 0
	v_lshlrev_b32_e32 v142, 16, v144
	v_and_b32_e32 v143, 0xffff0000, v144
	v_mul_f32_e32 v142, v196, v142
	v_mul_f32_e32 v143, v196, v143
	v_cvt_pk_bf16_f32 v144, v142, v143
	v_lshlrev_b32_e32 v142, 16, v145
	v_and_b32_e32 v143, 0xffff0000, v145
	v_mul_f32_e32 v142, v196, v142
	v_mul_f32_e32 v143, v196, v143
	v_cvt_pk_bf16_f32 v145, v142, v143
	v_lshlrev_b32_e32 v142, 16, v146
	v_and_b32_e32 v143, 0xffff0000, v146
	v_mul_f32_e32 v142, v196, v142
	v_mul_f32_e32 v143, v196, v143
	v_cvt_pk_bf16_f32 v146, v142, v143
	v_lshlrev_b32_e32 v142, 16, v147
	v_and_b32_e32 v143, 0xffff0000, v147
	v_mul_f32_e32 v142, v196, v142
	v_mul_f32_e32 v143, v196, v143
	v_cvt_pk_bf16_f32 v147, v142, v143
	global_store_dwordx4 v141, v[144:147], s[100:101]
	v_lshlrev_b32_e32 v142, 16, v148
	v_and_b32_e32 v143, 0xffff0000, v148
	v_mul_f32_e32 v142, v197, v142
	v_mul_f32_e32 v143, v197, v143
	v_cvt_pk_bf16_f32 v148, v142, v143
	v_lshlrev_b32_e32 v142, 16, v149
	v_and_b32_e32 v143, 0xffff0000, v149
	v_mul_f32_e32 v142, v197, v142
	v_mul_f32_e32 v143, v197, v143
	v_cvt_pk_bf16_f32 v149, v142, v143
	v_lshlrev_b32_e32 v142, 16, v150
	v_and_b32_e32 v143, 0xffff0000, v150
	v_mul_f32_e32 v142, v197, v142
	v_mul_f32_e32 v143, v197, v143
	v_cvt_pk_bf16_f32 v150, v142, v143
	v_lshlrev_b32_e32 v142, 16, v151
	v_and_b32_e32 v143, 0xffff0000, v151
	v_mul_f32_e32 v142, v197, v142
	v_mul_f32_e32 v143, v197, v143
	v_cvt_pk_bf16_f32 v151, v142, v143
	global_store_dwordx4 v141, v[148:151], s[100:101] offset:1024
	v_lshlrev_b32_e32 v142, 16, v152
	v_and_b32_e32 v143, 0xffff0000, v152
	v_mul_f32_e32 v142, v198, v142
	v_mul_f32_e32 v143, v198, v143
	v_cvt_pk_bf16_f32 v152, v142, v143
	v_lshlrev_b32_e32 v142, 16, v153
	v_and_b32_e32 v143, 0xffff0000, v153
	v_mul_f32_e32 v142, v198, v142
	v_mul_f32_e32 v143, v198, v143
	v_cvt_pk_bf16_f32 v153, v142, v143
	v_lshlrev_b32_e32 v142, 16, v154
	v_and_b32_e32 v143, 0xffff0000, v154
	v_mul_f32_e32 v142, v198, v142
	v_mul_f32_e32 v143, v198, v143
	v_cvt_pk_bf16_f32 v154, v142, v143
	v_lshlrev_b32_e32 v142, 16, v155
	v_and_b32_e32 v143, 0xffff0000, v155
	v_mul_f32_e32 v142, v198, v142
	v_mul_f32_e32 v143, v198, v143
	v_cvt_pk_bf16_f32 v155, v142, v143
	global_store_dwordx4 v141, v[152:155], s[100:101] offset:2048
	v_lshlrev_b32_e32 v142, 16, v156
	v_and_b32_e32 v143, 0xffff0000, v156
	v_mul_f32_e32 v142, v199, v142
	v_mul_f32_e32 v143, v199, v143
	v_cvt_pk_bf16_f32 v156, v142, v143
	v_lshlrev_b32_e32 v142, 16, v157
	v_and_b32_e32 v143, 0xffff0000, v157
	v_mul_f32_e32 v142, v199, v142
	v_mul_f32_e32 v143, v199, v143
	v_cvt_pk_bf16_f32 v157, v142, v143
	v_lshlrev_b32_e32 v142, 16, v158
	v_and_b32_e32 v143, 0xffff0000, v158
	v_mul_f32_e32 v142, v199, v142
	v_mul_f32_e32 v143, v199, v143
	v_cvt_pk_bf16_f32 v158, v142, v143
	v_lshlrev_b32_e32 v142, 16, v159
	v_and_b32_e32 v143, 0xffff0000, v159
	v_mul_f32_e32 v142, v199, v142
	v_mul_f32_e32 v143, v199, v143
	v_cvt_pk_bf16_f32 v159, v142, v143
	global_store_dwordx4 v141, v[156:159], s[100:101] offset:3072
	v_lshlrev_b32_e32 v142, 16, v160
	v_and_b32_e32 v143, 0xffff0000, v160
	v_mul_f32_e32 v142, v200, v142
	v_mul_f32_e32 v143, v200, v143
	v_cvt_pk_bf16_f32 v160, v142, v143
	v_lshlrev_b32_e32 v142, 16, v161
	v_and_b32_e32 v143, 0xffff0000, v161
	v_mul_f32_e32 v142, v200, v142
	v_mul_f32_e32 v143, v200, v143
	v_cvt_pk_bf16_f32 v161, v142, v143
	v_lshlrev_b32_e32 v142, 16, v162
	v_and_b32_e32 v143, 0xffff0000, v162
	v_mul_f32_e32 v142, v200, v142
	v_mul_f32_e32 v143, v200, v143
	v_cvt_pk_bf16_f32 v162, v142, v143
	v_lshlrev_b32_e32 v142, 16, v163
	v_and_b32_e32 v143, 0xffff0000, v163
	v_mul_f32_e32 v142, v200, v142
	v_mul_f32_e32 v143, v200, v143
	v_cvt_pk_bf16_f32 v163, v142, v143
	global_store_dwordx4 v141, v[160:163], s[98:99]
	v_lshlrev_b32_e32 v142, 16, v164
	v_and_b32_e32 v143, 0xffff0000, v164
	v_mul_f32_e32 v142, v201, v142
	v_mul_f32_e32 v143, v201, v143
	v_cvt_pk_bf16_f32 v164, v142, v143
	v_lshlrev_b32_e32 v142, 16, v165
	v_and_b32_e32 v143, 0xffff0000, v165
	v_mul_f32_e32 v142, v201, v142
	v_mul_f32_e32 v143, v201, v143
	v_cvt_pk_bf16_f32 v165, v142, v143
	v_lshlrev_b32_e32 v142, 16, v166
	v_and_b32_e32 v143, 0xffff0000, v166
	v_mul_f32_e32 v142, v201, v142
	v_mul_f32_e32 v143, v201, v143
	v_cvt_pk_bf16_f32 v166, v142, v143
	v_lshlrev_b32_e32 v142, 16, v167
	v_and_b32_e32 v143, 0xffff0000, v167
	v_mul_f32_e32 v142, v201, v142
	v_mul_f32_e32 v143, v201, v143
	v_cvt_pk_bf16_f32 v167, v142, v143
	global_store_dwordx4 v141, v[164:167], s[98:99] offset:1024
	v_lshlrev_b32_e32 v142, 16, v168
	v_and_b32_e32 v143, 0xffff0000, v168
	v_mul_f32_e32 v142, v202, v142
	v_mul_f32_e32 v143, v202, v143
	v_cvt_pk_bf16_f32 v168, v142, v143
	v_lshlrev_b32_e32 v142, 16, v169
	v_and_b32_e32 v143, 0xffff0000, v169
	v_mul_f32_e32 v142, v202, v142
	v_mul_f32_e32 v143, v202, v143
	v_cvt_pk_bf16_f32 v169, v142, v143
	v_lshlrev_b32_e32 v142, 16, v170
	v_and_b32_e32 v143, 0xffff0000, v170
	v_mul_f32_e32 v142, v202, v142
	v_mul_f32_e32 v143, v202, v143
	v_cvt_pk_bf16_f32 v170, v142, v143
	v_lshlrev_b32_e32 v142, 16, v171
	v_and_b32_e32 v143, 0xffff0000, v171
	v_mul_f32_e32 v142, v202, v142
	v_mul_f32_e32 v143, v202, v143
	v_cvt_pk_bf16_f32 v171, v142, v143
	global_store_dwordx4 v141, v[168:171], s[98:99] offset:2048
	v_lshlrev_b32_e32 v142, 16, v182
	v_and_b32_e32 v143, 0xffff0000, v182
	v_mul_f32_e32 v142, v203, v142
	v_mul_f32_e32 v143, v203, v143
	v_cvt_pk_bf16_f32 v182, v142, v143
	v_lshlrev_b32_e32 v142, 16, v183
	v_and_b32_e32 v143, 0xffff0000, v183
	v_mul_f32_e32 v142, v203, v142
	v_mul_f32_e32 v143, v203, v143
	v_cvt_pk_bf16_f32 v183, v142, v143
	v_lshlrev_b32_e32 v142, 16, v184
	v_and_b32_e32 v143, 0xffff0000, v184
	v_mul_f32_e32 v142, v203, v142
	v_mul_f32_e32 v143, v203, v143
	v_cvt_pk_bf16_f32 v184, v142, v143
	v_lshlrev_b32_e32 v142, 16, v185
	v_and_b32_e32 v143, 0xffff0000, v185
	v_mul_f32_e32 v142, v203, v142
	v_mul_f32_e32 v143, v203, v143
	v_cvt_pk_bf16_f32 v185, v142, v143
	global_store_dwordx4 v141, v[182:185], s[98:99] offset:3072
.Lsg_skip:
	s_cmpk_gt_i32 s92, 0x1ff
	s_cbranch_scc1 .LBB0_430
	v_readlane_b32 s0, v255, 45
	s_add_u32 s26, s24, 0x22579800
	v_readlane_b32 s1, v255, 46
	s_addc_u32 s27, s25, 0
	s_load_dwordx8 s[56:63], s[0:1], 0x40
	s_add_u32 s80, s24, 0x13c14200
	s_addc_u32 s81, s25, 0
	s_add_u32 s76, s24, 0x13a00200
	s_addc_u32 s77, s25, 0
	s_waitcnt lgkmcnt(0)
	s_add_u32 s93, s56, 0x5000
	s_addc_u32 s94, s57, 0
	s_add_u32 s95, s58, 0x5000
	s_load_dwordx2 s[84:85], s[0:1], 0x60
	s_addc_u32 s68, s59, 0
	s_add_u32 s69, s56, 0x4000
	s_addc_u32 s70, s57, 0
	s_add_u32 s71, s58, 0x4000
	s_addc_u32 s29, s59, 0
	s_branch .LBB0_257
.LBB0_256:
	s_or_b64 exec, exec, s[4:5]
	v_lshrrev_b32_e32 v140, 6, v177
	v_and_b32_e32 v141, 63, v177
	v_readfirstlane_b32 s98, v140
	v_lshlrev_b32_e32 v141, 4, v141
	s_lshl_b32 s98, s98, 4
	s_add_i32 s98, s98, s75
	s_mul_i32 s100, s98, 0x5200
	s_mul_hi_i32 s101, s98, 0x5200
	s_add_u32 s100, s82, s100
	s_addc_u32 s101, s83, s101
	s_lshl_b32 s99, s74, 10
	s_add_u32 s100, s100, s99
	s_addc_u32 s101, s101, 0
	s_waitcnt vmcnt(0)
	s_mov_b64 s[98:99], s[100:101]
	global_load_dwordx4 v[144:147], v141, s[100:101]
	s_add_u32 s100, s100, 0x5200
	s_addc_u32 s101, s101, 0
	global_load_dwordx4 v[148:151], v141, s[100:101]
	s_add_u32 s100, s100, 0x5200
	s_addc_u32 s101, s101, 0
	global_load_dwordx4 v[152:155], v141, s[100:101]
	s_add_u32 s100, s100, 0x5200
	s_addc_u32 s101, s101, 0
	global_load_dwordx4 v[156:159], v141, s[100:101]
	s_add_u32 s100, s100, 0x5200
	s_addc_u32 s101, s101, 0
	global_load_dwordx4 v[160:163], v141, s[100:101]
	s_add_u32 s100, s100, 0x5200
	s_addc_u32 s101, s101, 0
	global_load_dwordx4 v[164:167], v141, s[100:101]
	s_add_u32 s100, s100, 0x5200
	s_addc_u32 s101, s101, 0
	global_load_dwordx4 v[168:171], v141, s[100:101]
	s_add_u32 s100, s100, 0x5200
	s_addc_u32 s101, s101, 0
	global_load_dwordx4 v[182:185], v141, s[100:101]
	s_add_u32 s100, s100, 0x5200
	s_addc_u32 s101, s101, 0
	s_waitcnt vmcnt(7)
	v_readlane_b32 vcc_lo, v4, 0
	v_lshlrev_b32_e32 v142, 16, v144
	v_and_b32_e32 v143, 0xffff0000, v144
	v_mul_f32_e32 v142, vcc_lo, v142
	v_mul_f32_e32 v143, vcc_lo, v143
	v_cvt_pk_bf16_f32 v144, v142, v143
	v_lshlrev_b32_e32 v142, 16, v145
	v_and_b32_e32 v143, 0xffff0000, v145
	v_mul_f32_e32 v142, vcc_lo, v142
	v_mul_f32_e32 v143, vcc_lo, v143
	v_cvt_pk_bf16_f32 v145, v142, v143
	v_lshlrev_b32_e32 v142, 16, v146
	v_and_b32_e32 v143, 0xffff0000, v146
	v_mul_f32_e32 v142, vcc_lo, v142
	v_mul_f32_e32 v143, vcc_lo, v143
	v_cvt_pk_bf16_f32 v146, v142, v143
	v_lshlrev_b32_e32 v142, 16, v147
	v_and_b32_e32 v143, 0xffff0000, v147
	v_mul_f32_e32 v142, vcc_lo, v142
	v_mul_f32_e32 v143, vcc_lo, v143
	v_cvt_pk_bf16_f32 v147, v142, v143
	global_store_dwordx4 v141, v[144:147], s[98:99]
	s_add_u32 s98, s98, 0x5200
	s_addc_u32 s99, s99, 0
	s_waitcnt vmcnt(7)
	v_readlane_b32 vcc_lo, v4, 1
	v_lshlrev_b32_e32 v142, 16, v148
	v_and_b32_e32 v143, 0xffff0000, v148
	v_mul_f32_e32 v142, vcc_lo, v142
	v_mul_f32_e32 v143, vcc_lo, v143
	v_cvt_pk_bf16_f32 v148, v142, v143
	v_lshlrev_b32_e32 v142, 16, v149
	v_and_b32_e32 v143, 0xffff0000, v149
	v_mul_f32_e32 v142, vcc_lo, v142
	v_mul_f32_e32 v143, vcc_lo, v143
	v_cvt_pk_bf16_f32 v149, v142, v143
	v_lshlrev_b32_e32 v142, 16, v150
	v_and_b32_e32 v143, 0xffff0000, v150
	v_mul_f32_e32 v142, vcc_lo, v142
	v_mul_f32_e32 v143, vcc_lo, v143
	v_cvt_pk_bf16_f32 v150, v142, v143
	v_lshlrev_b32_e32 v142, 16, v151
	v_and_b32_e32 v143, 0xffff0000, v151
	v_mul_f32_e32 v142, vcc_lo, v142
	v_mul_f32_e32 v143, vcc_lo, v143
	v_cvt_pk_bf16_f32 v151, v142, v143
	global_store_dwordx4 v141, v[148:151], s[98:99]
	s_add_u32 s98, s98, 0x5200
	s_addc_u32 s99, s99, 0
	s_waitcnt vmcnt(7)
	v_readlane_b32 vcc_lo, v4, 2
	v_lshlrev_b32_e32 v142, 16, v152
	v_and_b32_e32 v143, 0xffff0000, v152
	v_mul_f32_e32 v142, vcc_lo, v142
	v_mul_f32_e32 v143, vcc_lo, v143
	v_cvt_pk_bf16_f32 v152, v142, v143
	v_lshlrev_b32_e32 v142, 16, v153
	v_and_b32_e32 v143, 0xffff0000, v153
	v_mul_f32_e32 v142, vcc_lo, v142
	v_mul_f32_e32 v143, vcc_lo, v143
	v_cvt_pk_bf16_f32 v153, v142, v143
	v_lshlrev_b32_e32 v142, 16, v154
	v_and_b32_e32 v143, 0xffff0000, v154
	v_mul_f32_e32 v142, vcc_lo, v142
	v_mul_f32_e32 v143, vcc_lo, v143
	v_cvt_pk_bf16_f32 v154, v142, v143
	v_lshlrev_b32_e32 v142, 16, v155
	v_and_b32_e32 v143, 0xffff0000, v155
	v_mul_f32_e32 v142, vcc_lo, v142
	v_mul_f32_e32 v143, vcc_lo, v143
	v_cvt_pk_bf16_f32 v155, v142, v143
	global_store_dwordx4 v141, v[152:155], s[98:99]
	s_add_u32 s98, s98, 0x5200
	s_addc_u32 s99, s99, 0
	s_waitcnt vmcnt(7)
	v_readlane_b32 vcc_lo, v4, 3
	v_lshlrev_b32_e32 v142, 16, v156
	v_and_b32_e32 v143, 0xffff0000, v156
	v_mul_f32_e32 v142, vcc_lo, v142
	v_mul_f32_e32 v143, vcc_lo, v143
	v_cvt_pk_bf16_f32 v156, v142, v143
	v_lshlrev_b32_e32 v142, 16, v157
	v_and_b32_e32 v143, 0xffff0000, v157
	v_mul_f32_e32 v142, vcc_lo, v142
	v_mul_f32_e32 v143, vcc_lo, v143
	v_cvt_pk_bf16_f32 v157, v142, v143
	v_lshlrev_b32_e32 v142, 16, v158
	v_and_b32_e32 v143, 0xffff0000, v158
	v_mul_f32_e32 v142, vcc_lo, v142
	v_mul_f32_e32 v143, vcc_lo, v143
	v_cvt_pk_bf16_f32 v158, v142, v143
	v_lshlrev_b32_e32 v142, 16, v159
	v_and_b32_e32 v143, 0xffff0000, v159
	v_mul_f32_e32 v142, vcc_lo, v142
	v_mul_f32_e32 v143, vcc_lo, v143
	v_cvt_pk_bf16_f32 v159, v142, v143
	global_store_dwordx4 v141, v[156:159], s[98:99]
	s_add_u32 s98, s98, 0x5200
	s_addc_u32 s99, s99, 0
	s_waitcnt vmcnt(7)
	v_readlane_b32 vcc_lo, v4, 4
	v_lshlrev_b32_e32 v142, 16, v160
	v_and_b32_e32 v143, 0xffff0000, v160
	v_mul_f32_e32 v142, vcc_lo, v142
	v_mul_f32_e32 v143, vcc_lo, v143
	v_cvt_pk_bf16_f32 v160, v142, v143
	v_lshlrev_b32_e32 v142, 16, v161
	v_and_b32_e32 v143, 0xffff0000, v161
	v_mul_f32_e32 v142, vcc_lo, v142
	v_mul_f32_e32 v143, vcc_lo, v143
	v_cvt_pk_bf16_f32 v161, v142, v143
	v_lshlrev_b32_e32 v142, 16, v162
	v_and_b32_e32 v143, 0xffff0000, v162
	v_mul_f32_e32 v142, vcc_lo, v142
	v_mul_f32_e32 v143, vcc_lo, v143
	v_cvt_pk_bf16_f32 v162, v142, v143
	v_lshlrev_b32_e32 v142, 16, v163
	v_and_b32_e32 v143, 0xffff0000, v163
	v_mul_f32_e32 v142, vcc_lo, v142
	v_mul_f32_e32 v143, vcc_lo, v143
	v_cvt_pk_bf16_f32 v163, v142, v143
	global_store_dwordx4 v141, v[160:163], s[98:99]
	s_add_u32 s98, s98, 0x5200
	s_addc_u32 s99, s99, 0
	s_waitcnt vmcnt(7)
	v_readlane_b32 vcc_lo, v4, 5
	v_lshlrev_b32_e32 v142, 16, v164
	v_and_b32_e32 v143, 0xffff0000, v164
	v_mul_f32_e32 v142, vcc_lo, v142
	v_mul_f32_e32 v143, vcc_lo, v143
	v_cvt_pk_bf16_f32 v164, v142, v143
	v_lshlrev_b32_e32 v142, 16, v165
	v_and_b32_e32 v143, 0xffff0000, v165
	v_mul_f32_e32 v142, vcc_lo, v142
	v_mul_f32_e32 v143, vcc_lo, v143
	v_cvt_pk_bf16_f32 v165, v142, v143
	v_lshlrev_b32_e32 v142, 16, v166
	v_and_b32_e32 v143, 0xffff0000, v166
	v_mul_f32_e32 v142, vcc_lo, v142
	v_mul_f32_e32 v143, vcc_lo, v143
	v_cvt_pk_bf16_f32 v166, v142, v143
	v_lshlrev_b32_e32 v142, 16, v167
	v_and_b32_e32 v143, 0xffff0000, v167
	v_mul_f32_e32 v142, vcc_lo, v142
	v_mul_f32_e32 v143, vcc_lo, v143
	v_cvt_pk_bf16_f32 v167, v142, v143
	global_store_dwordx4 v141, v[164:167], s[98:99]
	s_add_u32 s98, s98, 0x5200
	s_addc_u32 s99, s99, 0
	s_waitcnt vmcnt(7)
	v_readlane_b32 vcc_lo, v4, 6
	v_lshlrev_b32_e32 v142, 16, v168
	v_and_b32_e32 v143, 0xffff0000, v168
	v_mul_f32_e32 v142, vcc_lo, v142
	v_mul_f32_e32 v143, vcc_lo, v143
	v_cvt_pk_bf16_f32 v168, v142, v143
	v_lshlrev_b32_e32 v142, 16, v169
	v_and_b32_e32 v143, 0xffff0000, v169
	v_mul_f32_e32 v142, vcc_lo, v142
	v_mul_f32_e32 v143, vcc_lo, v143
	v_cvt_pk_bf16_f32 v169, v142, v143
	v_lshlrev_b32_e32 v142, 16, v170
	v_and_b32_e32 v143, 0xffff0000, v170
	v_mul_f32_e32 v142, vcc_lo, v142
	v_mul_f32_e32 v143, vcc_lo, v143
	v_cvt_pk_bf16_f32 v170, v142, v143
	v_lshlrev_b32_e32 v142, 16, v171
	v_and_b32_e32 v143, 0xffff0000, v171
	v_mul_f32_e32 v142, vcc_lo, v142
	v_mul_f32_e32 v143, vcc_lo, v143
	v_cvt_pk_bf16_f32 v171, v142, v143
	global_store_dwordx4 v141, v[168:171], s[98:99]
	s_add_u32 s98, s98, 0x5200
	s_addc_u32 s99, s99, 0
	s_waitcnt vmcnt(7)
	v_readlane_b32 vcc_lo, v4, 7
	v_lshlrev_b32_e32 v142, 16, v182
	v_and_b32_e32 v143, 0xffff0000, v182
	v_mul_f32_e32 v142, vcc_lo, v142
	v_mul_f32_e32 v143, vcc_lo, v143
	v_cvt_pk_bf16_f32 v182, v142, v143
	v_lshlrev_b32_e32 v142, 16, v183
	v_and_b32_e32 v143, 0xffff0000, v183
	v_mul_f32_e32 v142, vcc_lo, v142
	v_mul_f32_e32 v143, vcc_lo, v143
	v_cvt_pk_bf16_f32 v183, v142, v143
	v_lshlrev_b32_e32 v142, 16, v184
	v_and_b32_e32 v143, 0xffff0000, v184
	v_mul_f32_e32 v142, vcc_lo, v142
	v_mul_f32_e32 v143, vcc_lo, v143
	v_cvt_pk_bf16_f32 v184, v142, v143
	v_lshlrev_b32_e32 v142, 16, v185
	v_and_b32_e32 v143, 0xffff0000, v185
	v_mul_f32_e32 v142, vcc_lo, v142
	v_mul_f32_e32 v143, vcc_lo, v143
	v_cvt_pk_bf16_f32 v185, v142, v143
	global_store_dwordx4 v141, v[182:185], s[98:99]
	s_add_u32 s98, s98, 0x5200
	s_addc_u32 s99, s99, 0
	s_mov_b64 s[98:99], s[100:101]
	global_load_dwordx4 v[144:147], v141, s[100:101]
	s_add_u32 s100, s100, 0x5200
	s_addc_u32 s101, s101, 0
	global_load_dwordx4 v[148:151], v141, s[100:101]
	s_add_u32 s100, s100, 0x5200
	s_addc_u32 s101, s101, 0
	global_load_dwordx4 v[152:155], v141, s[100:101]
	s_add_u32 s100, s100, 0x5200
	s_addc_u32 s101, s101, 0
	global_load_dwordx4 v[156:159], v141, s[100:101]
	s_add_u32 s100, s100, 0x5200
	s_addc_u32 s101, s101, 0
	global_load_dwordx4 v[160:163], v141, s[100:101]
	s_add_u32 s100, s100, 0x5200
	s_addc_u32 s101, s101, 0
	global_load_dwordx4 v[164:167], v141, s[100:101]
	s_add_u32 s100, s100, 0x5200
	s_addc_u32 s101, s101, 0
	global_load_dwordx4 v[168:171], v141, s[100:101]
	s_add_u32 s100, s100, 0x5200
	s_addc_u32 s101, s101, 0
	global_load_dwordx4 v[182:185], v141, s[100:101]
	s_add_u32 s100, s100, 0x5200
	s_addc_u32 s101, s101, 0
	s_waitcnt vmcnt(7)
	v_readlane_b32 vcc_lo, v4, 8
	v_lshlrev_b32_e32 v142, 16, v144
	v_and_b32_e32 v143, 0xffff0000, v144
	v_mul_f32_e32 v142, vcc_lo, v142
	v_mul_f32_e32 v143, vcc_lo, v143
	v_cvt_pk_bf16_f32 v144, v142, v143
	v_lshlrev_b32_e32 v142, 16, v145
	v_and_b32_e32 v143, 0xffff0000, v145
	v_mul_f32_e32 v142, vcc_lo, v142
	v_mul_f32_e32 v143, vcc_lo, v143
	v_cvt_pk_bf16_f32 v145, v142, v143
	v_lshlrev_b32_e32 v142, 16, v146
	v_and_b32_e32 v143, 0xffff0000, v146
	v_mul_f32_e32 v142, vcc_lo, v142
	v_mul_f32_e32 v143, vcc_lo, v143
	v_cvt_pk_bf16_f32 v146, v142, v143
	v_lshlrev_b32_e32 v142, 16, v147
	v_and_b32_e32 v143, 0xffff0000, v147
	v_mul_f32_e32 v142, vcc_lo, v142
	v_mul_f32_e32 v143, vcc_lo, v143
	v_cvt_pk_bf16_f32 v147, v142, v143
	global_store_dwordx4 v141, v[144:147], s[98:99]
	s_add_u32 s98, s98, 0x5200
	s_addc_u32 s99, s99, 0
	s_waitcnt vmcnt(7)
	v_readlane_b32 vcc_lo, v4, 9
	v_lshlrev_b32_e32 v142, 16, v148
	v_and_b32_e32 v143, 0xffff0000, v148
	v_mul_f32_e32 v142, vcc_lo, v142
	v_mul_f32_e32 v143, vcc_lo, v143
	v_cvt_pk_bf16_f32 v148, v142, v143
	v_lshlrev_b32_e32 v142, 16, v149
	v_and_b32_e32 v143, 0xffff0000, v149
	v_mul_f32_e32 v142, vcc_lo, v142
	v_mul_f32_e32 v143, vcc_lo, v143
	v_cvt_pk_bf16_f32 v149, v142, v143
	v_lshlrev_b32_e32 v142, 16, v150
	v_and_b32_e32 v143, 0xffff0000, v150
	v_mul_f32_e32 v142, vcc_lo, v142
	v_mul_f32_e32 v143, vcc_lo, v143
	v_cvt_pk_bf16_f32 v150, v142, v143
	v_lshlrev_b32_e32 v142, 16, v151
	v_and_b32_e32 v143, 0xffff0000, v151
	v_mul_f32_e32 v142, vcc_lo, v142
	v_mul_f32_e32 v143, vcc_lo, v143
	v_cvt_pk_bf16_f32 v151, v142, v143
	global_store_dwordx4 v141, v[148:151], s[98:99]
	s_add_u32 s98, s98, 0x5200
	s_addc_u32 s99, s99, 0
	s_waitcnt vmcnt(7)
	v_readlane_b32 vcc_lo, v4, 10
	v_lshlrev_b32_e32 v142, 16, v152
	v_and_b32_e32 v143, 0xffff0000, v152
	v_mul_f32_e32 v142, vcc_lo, v142
	v_mul_f32_e32 v143, vcc_lo, v143
	v_cvt_pk_bf16_f32 v152, v142, v143
	v_lshlrev_b32_e32 v142, 16, v153
	v_and_b32_e32 v143, 0xffff0000, v153
	v_mul_f32_e32 v142, vcc_lo, v142
	v_mul_f32_e32 v143, vcc_lo, v143
	v_cvt_pk_bf16_f32 v153, v142, v143
	v_lshlrev_b32_e32 v142, 16, v154
	v_and_b32_e32 v143, 0xffff0000, v154
	v_mul_f32_e32 v142, vcc_lo, v142
	v_mul_f32_e32 v143, vcc_lo, v143
	v_cvt_pk_bf16_f32 v154, v142, v143
	v_lshlrev_b32_e32 v142, 16, v155
	v_and_b32_e32 v143, 0xffff0000, v155
	v_mul_f32_e32 v142, vcc_lo, v142
	v_mul_f32_e32 v143, vcc_lo, v143
	v_cvt_pk_bf16_f32 v155, v142, v143
	global_store_dwordx4 v141, v[152:155], s[98:99]
	s_add_u32 s98, s98, 0x5200
	s_addc_u32 s99, s99, 0
	s_waitcnt vmcnt(7)
	v_readlane_b32 vcc_lo, v4, 11
	v_lshlrev_b32_e32 v142, 16, v156
	v_and_b32_e32 v143, 0xffff0000, v156
	v_mul_f32_e32 v142, vcc_lo, v142
	v_mul_f32_e32 v143, vcc_lo, v143
	v_cvt_pk_bf16_f32 v156, v142, v143
	v_lshlrev_b32_e32 v142, 16, v157
	v_and_b32_e32 v143, 0xffff0000, v157
	v_mul_f32_e32 v142, vcc_lo, v142
	v_mul_f32_e32 v143, vcc_lo, v143
	v_cvt_pk_bf16_f32 v157, v142, v143
	v_lshlrev_b32_e32 v142, 16, v158
	v_and_b32_e32 v143, 0xffff0000, v158
	v_mul_f32_e32 v142, vcc_lo, v142
	v_mul_f32_e32 v143, vcc_lo, v143
	v_cvt_pk_bf16_f32 v158, v142, v143
	v_lshlrev_b32_e32 v142, 16, v159
	v_and_b32_e32 v143, 0xffff0000, v159
	v_mul_f32_e32 v142, vcc_lo, v142
	v_mul_f32_e32 v143, vcc_lo, v143
	v_cvt_pk_bf16_f32 v159, v142, v143
	global_store_dwordx4 v141, v[156:159], s[98:99]
	s_add_u32 s98, s98, 0x5200
	s_addc_u32 s99, s99, 0
	s_waitcnt vmcnt(7)
	v_readlane_b32 vcc_lo, v4, 12
	v_lshlrev_b32_e32 v142, 16, v160
	v_and_b32_e32 v143, 0xffff0000, v160
	v_mul_f32_e32 v142, vcc_lo, v142
	v_mul_f32_e32 v143, vcc_lo, v143
	v_cvt_pk_bf16_f32 v160, v142, v143
	v_lshlrev_b32_e32 v142, 16, v161
	v_and_b32_e32 v143, 0xffff0000, v161
	v_mul_f32_e32 v142, vcc_lo, v142
	v_mul_f32_e32 v143, vcc_lo, v143
	v_cvt_pk_bf16_f32 v161, v142, v143
	v_lshlrev_b32_e32 v142, 16, v162
	v_and_b32_e32 v143, 0xffff0000, v162
	v_mul_f32_e32 v142, vcc_lo, v142
	v_mul_f32_e32 v143, vcc_lo, v143
	v_cvt_pk_bf16_f32 v162, v142, v143
	v_lshlrev_b32_e32 v142, 16, v163
	v_and_b32_e32 v143, 0xffff0000, v163
	v_mul_f32_e32 v142, vcc_lo, v142
	v_mul_f32_e32 v143, vcc_lo, v143
	v_cvt_pk_bf16_f32 v163, v142, v143
	global_store_dwordx4 v141, v[160:163], s[98:99]
	s_add_u32 s98, s98, 0x5200
	s_addc_u32 s99, s99, 0
	s_waitcnt vmcnt(7)
	v_readlane_b32 vcc_lo, v4, 13
	v_lshlrev_b32_e32 v142, 16, v164
	v_and_b32_e32 v143, 0xffff0000, v164
	v_mul_f32_e32 v142, vcc_lo, v142
	v_mul_f32_e32 v143, vcc_lo, v143
	v_cvt_pk_bf16_f32 v164, v142, v143
	v_lshlrev_b32_e32 v142, 16, v165
	v_and_b32_e32 v143, 0xffff0000, v165
	v_mul_f32_e32 v142, vcc_lo, v142
	v_mul_f32_e32 v143, vcc_lo, v143
	v_cvt_pk_bf16_f32 v165, v142, v143
	v_lshlrev_b32_e32 v142, 16, v166
	v_and_b32_e32 v143, 0xffff0000, v166
	v_mul_f32_e32 v142, vcc_lo, v142
	v_mul_f32_e32 v143, vcc_lo, v143
	v_cvt_pk_bf16_f32 v166, v142, v143
	v_lshlrev_b32_e32 v142, 16, v167
	v_and_b32_e32 v143, 0xffff0000, v167
	v_mul_f32_e32 v142, vcc_lo, v142
	v_mul_f32_e32 v143, vcc_lo, v143
	v_cvt_pk_bf16_f32 v167, v142, v143
	global_store_dwordx4 v141, v[164:167], s[98:99]
	s_add_u32 s98, s98, 0x5200
	s_addc_u32 s99, s99, 0
	s_waitcnt vmcnt(7)
	v_readlane_b32 vcc_lo, v4, 14
	v_lshlrev_b32_e32 v142, 16, v168
	v_and_b32_e32 v143, 0xffff0000, v168
	v_mul_f32_e32 v142, vcc_lo, v142
	v_mul_f32_e32 v143, vcc_lo, v143
	v_cvt_pk_bf16_f32 v168, v142, v143
	v_lshlrev_b32_e32 v142, 16, v169
	v_and_b32_e32 v143, 0xffff0000, v169
	v_mul_f32_e32 v142, vcc_lo, v142
	v_mul_f32_e32 v143, vcc_lo, v143
	v_cvt_pk_bf16_f32 v169, v142, v143
	v_lshlrev_b32_e32 v142, 16, v170
	v_and_b32_e32 v143, 0xffff0000, v170
	v_mul_f32_e32 v142, vcc_lo, v142
	v_mul_f32_e32 v143, vcc_lo, v143
	v_cvt_pk_bf16_f32 v170, v142, v143
	v_lshlrev_b32_e32 v142, 16, v171
	v_and_b32_e32 v143, 0xffff0000, v171
	v_mul_f32_e32 v142, vcc_lo, v142
	v_mul_f32_e32 v143, vcc_lo, v143
	v_cvt_pk_bf16_f32 v171, v142, v143
	global_store_dwordx4 v141, v[168:171], s[98:99]
	s_add_u32 s98, s98, 0x5200
	s_addc_u32 s99, s99, 0
	s_waitcnt vmcnt(7)
	v_readlane_b32 vcc_lo, v4, 15
	v_lshlrev_b32_e32 v142, 16, v182
	v_and_b32_e32 v143, 0xffff0000, v182
	v_mul_f32_e32 v142, vcc_lo, v142
	v_mul_f32_e32 v143, vcc_lo, v143
	v_cvt_pk_bf16_f32 v182, v142, v143
	v_lshlrev_b32_e32 v142, 16, v183
	v_and_b32_e32 v143, 0xffff0000, v183
	v_mul_f32_e32 v142, vcc_lo, v142
	v_mul_f32_e32 v143, vcc_lo, v143
	v_cvt_pk_bf16_f32 v183, v142, v143
	v_lshlrev_b32_e32 v142, 16, v184
	v_and_b32_e32 v143, 0xffff0000, v184
	v_mul_f32_e32 v142, vcc_lo, v142
	v_mul_f32_e32 v143, vcc_lo, v143
	v_cvt_pk_bf16_f32 v184, v142, v143
	v_lshlrev_b32_e32 v142, 16, v185
	v_and_b32_e32 v143, 0xffff0000, v185
	v_mul_f32_e32 v142, vcc_lo, v142
	v_mul_f32_e32 v143, vcc_lo, v143
	v_cvt_pk_bf16_f32 v185, v142, v143
	global_store_dwordx4 v141, v[182:185], s[98:99]
	s_add_u32 s98, s98, 0x5200
	s_addc_u32 s99, s99, 0
	v_readlane_b32 s74, v255, 28
	v_readlane_b32 s75, v255, 29
	s_waitcnt lgkmcnt(0)
	s_barrier
	s_load_dword s0, s[74:75], 0x0
	s_waitcnt lgkmcnt(0)
	s_add_i32 s92, s0, s92
	s_cmpk_gt_i32 s92, 0x1ff
	s_cbranch_scc1 .LBB0_430
